# k11 + FFN-in K-loop LDS-DMA via saddr form and B-fragment reads off one base VGPR (no VALU in the load segments)
# baseline (speedup 1.0000x reference)
; #define PG8_STAGE(bufoff, gbase, voff) do { _Pragma("unroll") for (int _i = 0; _i < 2; ++_i) \
;         __builtin_amdgcn_global_load_lds((const unsigned*)((const char*)(gbase) + (voff)[_i]), (PG8_LAS unsigned*)(lds + (bufoff) + ldsw + _i * 8192), 16, 0, 0); } while (0)
; #define PG8_LDA(dst, b, h) do { _Pragma("unroll") for (int m = 0; m < 4; ++m) _Pragma("unroll") for (int k = 0; k < 2; ++k) dst[m][k] = *(const PG8_LAS bf16x8*)(lds + PG8_SA(b, h) + aoff + m * 2048 + k * 1024); } while (0)
; #define PG8_LDB(dst, b, h) do { _Pragma("unroll") for (int n = 0; n < 2; ++n) _Pragma("unroll") for (int k = 0; k < 2; ++k) dst[n][k] = *(const PG8_LAS bf16x8*)(lds + PG8_SB(b, h) + boff + n * 2048 + k * 1024); } while (0)
; #define PG8_WAIT_V(n) asm volatile("s_waitcnt vmcnt(" #n ")" ::: "memory")
; #define PG8_WAIT_L(n) asm volatile("s_waitcnt lgkmcnt(" #n ")" ::: "memory")
; #define PG8_BAR __builtin_amdgcn_s_barrier()
; #define PG8_SCHED __builtin_amdgcn_sched_barrier(0)
; template <class Epi, class Sched, bool ALIGN_EPI = false, bool SP2 = false>
; __device__ __forceinline__ void gemm_phase(PG8_LAS unsigned char* lds, const Gemm g, const Sched S, const Epi E) {
;     ...
;     f32x4 acc[2][2][4][2];
; #pragma unroll
;     for (int a = 0; a < 2; ++a)
; #pragma unroll
;         for (int b = 0; b < 2; ++b)
; #pragma unroll
;             for (int m = 0; m < 4; ++m)
; #pragma unroll
;                 for (int n = 0; n < 2; ++n) acc[a][b][m][n] = (f32x4){0.f, 0.f, 0.f, 0.f};
;     ...
;         const bool has_next = S.next(ui + 1, nxt);
;         const char* nA = has_next ? (const char*)g.A + (size_t)nxt.pm * tstep : cA; const char* nB = has_next ? (const char*)g.Bt + (size_t)nxt.pn * tstep : cB;
;         for (int t = 0; t < nt; t += 2) {
;             const bool last = (t == nt - 2);
;             const char* a1 = cA + (size_t)(t + 1) * kstep;
;             const char* a2 = last ? nA : cA + (size_t)(t + 2) * kstep; const char* b2 = last ? nB : cB + (size_t)(t + 2) * kstep;
;             const char* a3 = a2 + kstep; const char* b3 = b2 + kstep;
;             if (last && has_next) S.a_ready(nxt);
;             if constexpr (SP2) {
;             PG8_LDB(B0, 0, 0); PG8_LDB(B1, 0, 1); PG8_SCHED; PG8_LDA(At, 0, 0); PG8_STAGE(PG8_SA(1, 1), a1 + hstep, voffA);
;             PG8_WAIT_V(8); PG8_WAIT_L(0); PG8_BAR; PG8_MMA(0, 0, At, B0); PG8_MMA(0, 1, At, B1); PG8_BAR; PG8_SCHED;
.LBB0_192:
	s_ashr_i32 s45, s44, 31
	s_lshl_b64 s[14:15], s[44:45], 20
	s_add_u32 s50, s3, s14
	s_addc_u32 s51, s33, s15
	s_and_b64 s[14:15], s[36:37], exec
	s_cselect_b32 s45, s51, s57
	s_cselect_b32 vcc_lo, s50, s56
	s_ashr_i32 s43, s42, 31
	s_lshl_b64 s[14:15], s[42:43], 20
	s_add_u32 s52, s66, s14
	s_addc_u32 s53, s67, s15
	s_and_b64 s[14:15], s[36:37], exec
	s_cselect_b32 s43, s53, s59
	s_cselect_b32 vcc_hi, s52, s58
	s_add_u32 s56, s56, 0x80080
	s_addc_u32 s57, s57, 0
	s_add_u32 s14, s58, 0x100
	v_mov_b32_e32 v2, 0
	s_addc_u32 s15, s59, 0
	s_mov_b32 s24, -2
	v_mov_b32_e32 v3, v2
	v_mov_b32_e32 v4, v2
	v_mov_b32_e32 v5, v2
	v_mov_b32_e32 v10, v2
	v_mov_b32_e32 v11, v2
	v_mov_b32_e32 v12, v2
	v_mov_b32_e32 v13, v2
	v_mov_b32_e32 v18, v2
	v_mov_b32_e32 v19, v2
	v_mov_b32_e32 v20, v2
	v_mov_b32_e32 v21, v2
	s_waitcnt lgkmcnt(0)
	v_mov_b32_e32 v26, v2
	v_mov_b32_e32 v27, v2
	v_mov_b32_e32 v28, v2
	v_mov_b32_e32 v29, v2
	v_mov_b32_e32 v34, v2
	v_mov_b32_e32 v35, v2
	v_mov_b32_e32 v36, v2
	v_mov_b32_e32 v37, v2
	v_mov_b32_e32 v42, v2
	v_mov_b32_e32 v43, v2
	v_mov_b32_e32 v44, v2
	v_mov_b32_e32 v45, v2
	v_mov_b32_e32 v50, v2
	v_mov_b32_e32 v51, v2
	v_mov_b32_e32 v52, v2
	v_mov_b32_e32 v53, v2
	v_mov_b32_e32 v58, v2
	v_mov_b32_e32 v59, v2
	v_mov_b32_e32 v60, v2
	v_mov_b32_e32 v61, v2
	v_mov_b32_e32 v6, v2
	v_mov_b32_e32 v7, v2
	v_mov_b32_e32 v8, v2
	v_mov_b32_e32 v9, v2
	v_mov_b32_e32 v14, v2
	v_mov_b32_e32 v15, v2
	v_mov_b32_e32 v16, v2
	v_mov_b32_e32 v17, v2
	v_mov_b32_e32 v22, v2
	v_mov_b32_e32 v23, v2
	v_mov_b32_e32 v24, v2
	v_mov_b32_e32 v25, v2
	v_mov_b32_e32 v30, v2
	v_mov_b32_e32 v31, v2
	v_mov_b32_e32 v32, v2
	v_mov_b32_e32 v33, v2
	v_mov_b32_e32 v38, v2
	v_mov_b32_e32 v39, v2
	v_mov_b32_e32 v40, v2
	v_mov_b32_e32 v41, v2
	v_mov_b32_e32 v46, v2
	v_mov_b32_e32 v47, v2
	v_mov_b32_e32 v48, v2
	v_mov_b32_e32 v49, v2
	v_mov_b32_e32 v54, v2
	v_mov_b32_e32 v55, v2
	v_mov_b32_e32 v56, v2
	v_mov_b32_e32 v57, v2
	v_mov_b32_e32 v62, v2
	v_mov_b32_e32 v63, v2
	v_mov_b32_e32 v64, v2
	v_mov_b32_e32 v65, v2
	v_mov_b32_e32 v66, v2
	v_mov_b32_e32 v67, v2
	v_mov_b32_e32 v68, v2
	v_mov_b32_e32 v69, v2
	v_mov_b32_e32 v74, v2
	v_mov_b32_e32 v75, v2
	v_mov_b32_e32 v76, v2
	v_mov_b32_e32 v77, v2
	v_mov_b32_e32 v82, v2
	v_mov_b32_e32 v83, v2
	v_mov_b32_e32 v84, v2
	v_mov_b32_e32 v85, v2
	v_mov_b32_e32 v90, v2
	v_mov_b32_e32 v91, v2
	v_mov_b32_e32 v92, v2
	v_mov_b32_e32 v93, v2
	v_mov_b32_e32 v98, v2
	v_mov_b32_e32 v99, v2
	v_mov_b32_e32 v100, v2
	v_mov_b32_e32 v101, v2
	v_mov_b32_e32 v106, v2
	v_mov_b32_e32 v107, v2
	v_mov_b32_e32 v108, v2
	v_mov_b32_e32 v109, v2
	v_mov_b32_e32 v114, v2
	v_mov_b32_e32 v115, v2
	v_mov_b32_e32 v116, v2
	v_mov_b32_e32 v117, v2
	v_mov_b32_e32 v122, v2
	v_mov_b32_e32 v123, v2
	v_mov_b32_e32 v124, v2
	v_mov_b32_e32 v125, v2
	v_mov_b32_e32 v70, v2
	v_mov_b32_e32 v71, v2
	v_mov_b32_e32 v72, v2
	v_mov_b32_e32 v73, v2
	v_mov_b32_e32 v78, v2
	v_mov_b32_e32 v79, v2
	v_mov_b32_e32 v80, v2
	v_mov_b32_e32 v81, v2
	v_mov_b32_e32 v86, v2
	v_mov_b32_e32 v87, v2
	v_mov_b32_e32 v88, v2
	v_mov_b32_e32 v89, v2
	v_mov_b32_e32 v94, v2
	v_mov_b32_e32 v95, v2
	v_mov_b32_e32 v96, v2
	v_mov_b32_e32 v97, v2
	v_mov_b32_e32 v102, v2
	v_mov_b32_e32 v103, v2
	v_mov_b32_e32 v104, v2
	v_mov_b32_e32 v105, v2
	v_mov_b32_e32 v110, v2
	v_mov_b32_e32 v111, v2
	v_mov_b32_e32 v112, v2
	v_mov_b32_e32 v113, v2
	v_mov_b32_e32 v118, v2
	v_mov_b32_e32 v119, v2
	v_mov_b32_e32 v120, v2
	v_mov_b32_e32 v121, v2
	v_mov_b32_e32 v126, v2
	v_mov_b32_e32 v127, v2
	v_mov_b32_e32 v128, v2
	v_mov_b32_e32 v129, v2
	v_add_u32_e32 v141, 0x10000, v143
.LBB0_193:
	s_add_u32 s25, s56, 0xfff80080
	s_addc_u32 s26, s57, -1
	s_add_i32 s27, 0, 0x10000
	s_cmp_eq_u32 s24, 28
	s_cselect_b32 s65, s45, s26
	s_cselect_b32 s64, vcc_lo, s25
	s_cselect_b32 s59, s43, s15
	s_cselect_b32 s58, vcc_hi, s14
	s_add_i32 s25, 0, 0x14000
	ds_read_b128 v[146:149], v141
	ds_read_b128 v[150:153], v141 offset:1024
	ds_read_b128 v[154:157], v141 offset:2048
	ds_read_b128 v[158:161], v141 offset:3072
	ds_read_b128 v[168:171], v141 offset:16384
	ds_read_b128 v[172:175], v141 offset:17408
	ds_read_b128 v[176:179], v141 offset:18432
	ds_read_b128 v[180:183], v141 offset:19456
	s_add_i32 m0, s75, 0xc000
	ds_read_b128 v[184:187], v145
	ds_read_b128 v[188:191], v145 offset:1024
	ds_read_b128 v[192:195], v145 offset:2048
	ds_read_b128 v[196:199], v145 offset:3072
	ds_read_b128 v[200:203], v145 offset:4096
	ds_read_b128 v[224:227], v145 offset:5120
	ds_read_b128 v[228:231], v145 offset:6144
	ds_read_b128 v[232:235], v145 offset:7168
	global_load_lds_dwordx4 v136, s[56:57]
	s_add_i32 m0, s75, 0xe000
	s_nop 0
	global_load_lds_dwordx4 v138, s[56:57]
	s_waitcnt vmcnt(8)
	s_waitcnt lgkmcnt(0)
	s_barrier
; #define PG8_STAGE(bufoff, gbase, voff) do { _Pragma("unroll") for (int _i = 0; _i < 2; ++_i) \
;         __builtin_amdgcn_global_load_lds((const unsigned*)((const char*)(gbase) + (voff)[_i]), (PG8_LAS unsigned*)(lds + (bufoff) + ldsw + _i * 8192), 16, 0, 0); } while (0)
; #define PG8_LDA(dst, b, h) do { _Pragma("unroll") for (int m = 0; m < 4; ++m) _Pragma("unroll") for (int k = 0; k < 2; ++k) dst[m][k] = *(const PG8_LAS bf16x8*)(lds + PG8_SA(b, h) + aoff + m * 2048 + k * 1024); } while (0)
; #define PG8_MMA(ai, bj, At, Bt) do { __builtin_amdgcn_s_setprio(1); _Pragma("unroll") for (int m = 0; m < 4; ++m) _Pragma("unroll") for (int n = 0; n < 2; ++n) _Pragma("unroll") for (int k = 0; k < 2; ++k) \
;         acc[ai][bj][m][n] = __builtin_amdgcn_mfma_f32_16x16x32_bf16(Bt[n][k], At[m][k], acc[ai][bj][m][n], 0, 0, 0); __builtin_amdgcn_s_setprio(0); } while (0)
; #define PG8_WAIT_V(n) asm volatile("s_waitcnt vmcnt(" #n ")" ::: "memory")
; #define PG8_WAIT_L(n) asm volatile("s_waitcnt lgkmcnt(" #n ")" ::: "memory")
; #define PG8_BAR __builtin_amdgcn_s_barrier()
; #define PG8_SCHED __builtin_amdgcn_sched_barrier(0)
; template <class Epi, class Sched, bool ALIGN_EPI = false, bool SP2 = false>
; __device__ __forceinline__ void gemm_phase(PG8_LAS unsigned char* lds, const Gemm g, const Sched S, const Epi E) {
;     ...
;             PG8_WAIT_V(8); PG8_WAIT_L(0); PG8_BAR; PG8_MMA(0, 0, At, B0); PG8_MMA(0, 1, At, B1); PG8_BAR; PG8_SCHED;
;             PG8_LDA(At, 0, 1); PG8_STAGE(PG8_SB(0, 0), b2, voffB); PG8_STAGE(PG8_SB(0, 1), b2 + hstep, voffB); PG8_STAGE(PG8_SA(0, 0), a2, voffA);
;             PG8_WAIT_V(8); PG8_WAIT_L(0); PG8_BAR; PG8_MMA(1, 0, At, B0); PG8_MMA(1, 1, At, B1); PG8_BAR; PG8_SCHED;
	s_setprio 1
	v_mfma_f32_16x16x32_bf16 v[126:129], v[146:149], v[184:187], v[126:129]
	v_mfma_f32_16x16x32_bf16 v[126:129], v[150:153], v[188:191], v[126:129]
	v_mfma_f32_16x16x32_bf16 v[118:121], v[154:157], v[184:187], v[118:121]
	v_mfma_f32_16x16x32_bf16 v[118:121], v[158:161], v[188:191], v[118:121]
	v_mfma_f32_16x16x32_bf16 v[110:113], v[146:149], v[192:195], v[110:113]
	v_mfma_f32_16x16x32_bf16 v[110:113], v[150:153], v[196:199], v[110:113]
	v_mfma_f32_16x16x32_bf16 v[102:105], v[154:157], v[192:195], v[102:105]
	v_mfma_f32_16x16x32_bf16 v[102:105], v[158:161], v[196:199], v[102:105]
	v_mfma_f32_16x16x32_bf16 v[94:97], v[146:149], v[200:203], v[94:97]
	v_mfma_f32_16x16x32_bf16 v[94:97], v[150:153], v[224:227], v[94:97]
	v_mfma_f32_16x16x32_bf16 v[86:89], v[154:157], v[200:203], v[86:89]
	v_mfma_f32_16x16x32_bf16 v[86:89], v[158:161], v[224:227], v[86:89]
	v_mfma_f32_16x16x32_bf16 v[78:81], v[146:149], v[228:231], v[78:81]
	v_mfma_f32_16x16x32_bf16 v[78:81], v[150:153], v[232:235], v[78:81]
	v_mfma_f32_16x16x32_bf16 v[70:73], v[154:157], v[228:231], v[70:73]
	v_mfma_f32_16x16x32_bf16 v[70:73], v[158:161], v[232:235], v[70:73]
	v_mfma_f32_16x16x32_bf16 v[122:125], v[168:171], v[184:187], v[122:125]
	v_mfma_f32_16x16x32_bf16 v[122:125], v[172:175], v[188:191], v[122:125]
	v_mfma_f32_16x16x32_bf16 v[114:117], v[176:179], v[184:187], v[114:117]
	v_mfma_f32_16x16x32_bf16 v[114:117], v[180:183], v[188:191], v[114:117]
	v_mfma_f32_16x16x32_bf16 v[106:109], v[168:171], v[192:195], v[106:109]
	v_mfma_f32_16x16x32_bf16 v[106:109], v[172:175], v[196:199], v[106:109]
	v_mfma_f32_16x16x32_bf16 v[98:101], v[176:179], v[192:195], v[98:101]
	v_mfma_f32_16x16x32_bf16 v[98:101], v[180:183], v[196:199], v[98:101]
	v_mfma_f32_16x16x32_bf16 v[90:93], v[168:171], v[200:203], v[90:93]
	v_mfma_f32_16x16x32_bf16 v[90:93], v[172:175], v[224:227], v[90:93]
	v_mfma_f32_16x16x32_bf16 v[82:85], v[176:179], v[200:203], v[82:85]
	v_mfma_f32_16x16x32_bf16 v[82:85], v[180:183], v[224:227], v[82:85]
	v_mfma_f32_16x16x32_bf16 v[74:77], v[168:171], v[228:231], v[74:77]
	v_mfma_f32_16x16x32_bf16 v[74:77], v[172:175], v[232:235], v[74:77]
	v_mfma_f32_16x16x32_bf16 v[66:69], v[176:179], v[228:231], v[66:69]
	v_mfma_f32_16x16x32_bf16 v[66:69], v[180:183], v[232:235], v[66:69]
	s_setprio 0
	s_barrier
	s_add_i32 s26, s27, s74
	s_mov_b32 m0, s26
	ds_read_b128 v[184:187], v145 offset:16384
	ds_read_b128 v[188:191], v145 offset:17408
	ds_read_b128 v[192:195], v145 offset:18432
	ds_read_b128 v[196:199], v145 offset:19456
	ds_read_b128 v[200:203], v145 offset:20480
	ds_read_b128 v[224:227], v145 offset:21504
	ds_read_b128 v[228:231], v145 offset:22528
	ds_read_b128 v[232:235], v145 offset:23552
	global_load_lds_dwordx4 v0, s[58:59]
	s_add_i32 m0, s26, 0x2000
	s_add_u32 s26, s58, 0x80000
	s_addc_u32 s27, s59, 0
	s_add_i32 s25, s25, s74
	global_load_lds_dwordx4 v130, s[58:59]
	s_mov_b32 m0, s25
	s_nop 0
	global_load_lds_dwordx4 v0, s[26:27]
	s_add_i32 m0, s25, 0x2000
	s_nop 0
	global_load_lds_dwordx4 v130, s[26:27]
	s_mov_b32 m0, s75
	s_nop 0
	global_load_lds_dwordx4 v134, s[64:65]
	s_mov_b32 m0, s21
	s_nop 0
	global_load_lds_dwordx4 v132, s[64:65]
	s_waitcnt vmcnt(8)
	s_waitcnt lgkmcnt(0)
	s_barrier
	s_setprio 1
	v_mfma_f32_16x16x32_bf16 v[62:65], v[146:149], v[184:187], v[62:65]
	v_mfma_f32_16x16x32_bf16 v[62:65], v[150:153], v[188:191], v[62:65]
	v_mfma_f32_16x16x32_bf16 v[54:57], v[154:157], v[184:187], v[54:57]
	v_mfma_f32_16x16x32_bf16 v[54:57], v[158:161], v[188:191], v[54:57]
	v_mfma_f32_16x16x32_bf16 v[46:49], v[146:149], v[192:195], v[46:49]
	v_mfma_f32_16x16x32_bf16 v[46:49], v[150:153], v[196:199], v[46:49]
	v_mfma_f32_16x16x32_bf16 v[38:41], v[154:157], v[192:195], v[38:41]
	v_mfma_f32_16x16x32_bf16 v[38:41], v[158:161], v[196:199], v[38:41]
	v_mfma_f32_16x16x32_bf16 v[30:33], v[146:149], v[200:203], v[30:33]
	v_mfma_f32_16x16x32_bf16 v[30:33], v[150:153], v[224:227], v[30:33]
	v_mfma_f32_16x16x32_bf16 v[22:25], v[154:157], v[200:203], v[22:25]
	v_mfma_f32_16x16x32_bf16 v[22:25], v[158:161], v[224:227], v[22:25]
	v_mfma_f32_16x16x32_bf16 v[14:17], v[146:149], v[228:231], v[14:17]
	v_mfma_f32_16x16x32_bf16 v[14:17], v[150:153], v[232:235], v[14:17]
	v_mfma_f32_16x16x32_bf16 v[6:9], v[154:157], v[228:231], v[6:9]
	v_mfma_f32_16x16x32_bf16 v[6:9], v[158:161], v[232:235], v[6:9]
	v_mfma_f32_16x16x32_bf16 v[58:61], v[168:171], v[184:187], v[58:61]
	v_mfma_f32_16x16x32_bf16 v[58:61], v[172:175], v[188:191], v[58:61]
	v_mfma_f32_16x16x32_bf16 v[50:53], v[176:179], v[184:187], v[50:53]
	v_mfma_f32_16x16x32_bf16 v[50:53], v[180:183], v[188:191], v[50:53]
	v_mfma_f32_16x16x32_bf16 v[42:45], v[168:171], v[192:195], v[42:45]
	v_mfma_f32_16x16x32_bf16 v[42:45], v[172:175], v[196:199], v[42:45]
	v_mfma_f32_16x16x32_bf16 v[34:37], v[176:179], v[192:195], v[34:37]
	v_mfma_f32_16x16x32_bf16 v[34:37], v[180:183], v[196:199], v[34:37]
	v_mfma_f32_16x16x32_bf16 v[26:29], v[168:171], v[200:203], v[26:29]
	v_mfma_f32_16x16x32_bf16 v[26:29], v[172:175], v[224:227], v[26:29]
	v_mfma_f32_16x16x32_bf16 v[18:21], v[176:179], v[200:203], v[18:21]
	v_mfma_f32_16x16x32_bf16 v[18:21], v[180:183], v[224:227], v[18:21]
	v_mfma_f32_16x16x32_bf16 v[10:13], v[168:171], v[228:231], v[10:13]
	v_mfma_f32_16x16x32_bf16 v[10:13], v[172:175], v[232:235], v[10:13]
	v_mfma_f32_16x16x32_bf16 v[2:5], v[176:179], v[228:231], v[2:5]
	v_mfma_f32_16x16x32_bf16 v[2:5], v[180:183], v[232:235], v[2:5]
	s_setprio 0
	s_barrier
; #define PG8_STAGE(bufoff, gbase, voff) do { _Pragma("unroll") for (int _i = 0; _i < 2; ++_i) \
;         __builtin_amdgcn_global_load_lds((const unsigned*)((const char*)(gbase) + (voff)[_i]), (PG8_LAS unsigned*)(lds + (bufoff) + ldsw + _i * 8192), 16, 0, 0); } while (0)
; #define PG8_LDA(dst, b, h) do { _Pragma("unroll") for (int m = 0; m < 4; ++m) _Pragma("unroll") for (int k = 0; k < 2; ++k) dst[m][k] = *(const PG8_LAS bf16x8*)(lds + PG8_SA(b, h) + aoff + m * 2048 + k * 1024); } while (0)
; #define PG8_LDB(dst, b, h) do { _Pragma("unroll") for (int n = 0; n < 2; ++n) _Pragma("unroll") for (int k = 0; k < 2; ++k) dst[n][k] = *(const PG8_LAS bf16x8*)(lds + PG8_SB(b, h) + boff + n * 2048 + k * 1024); } while (0)
; #define PG8_MMA(ai, bj, At, Bt) do { __builtin_amdgcn_s_setprio(1); _Pragma("unroll") for (int m = 0; m < 4; ++m) _Pragma("unroll") for (int n = 0; n < 2; ++n) _Pragma("unroll") for (int k = 0; k < 2; ++k) \
;         acc[ai][bj][m][n] = __builtin_amdgcn_mfma_f32_16x16x32_bf16(Bt[n][k], At[m][k], acc[ai][bj][m][n], 0, 0, 0); __builtin_amdgcn_s_setprio(0); } while (0)
; #define PG8_WAIT_V(n) asm volatile("s_waitcnt vmcnt(" #n ")" ::: "memory")
; #define PG8_WAIT_L(n) asm volatile("s_waitcnt lgkmcnt(" #n ")" ::: "memory")
; #define PG8_BAR __builtin_amdgcn_s_barrier()
; #define PG8_SCHED __builtin_amdgcn_sched_barrier(0)
; template <class Epi, class Sched, bool ALIGN_EPI = false, bool SP2 = false>
; __device__ __forceinline__ void gemm_phase(PG8_LAS unsigned char* lds, const Gemm g, const Sched S, const Epi E) {
;     ...
;             PG8_LDB(B0, 1, 0); PG8_LDB(B1, 1, 1); PG8_SCHED; PG8_LDA(At, 1, 0); PG8_STAGE(PG8_SA(0, 1), a2 + hstep, voffA);
;             PG8_WAIT_V(8); PG8_WAIT_L(0); PG8_BAR; PG8_MMA(0, 0, At, B0); PG8_MMA(0, 1, At, B1); PG8_BAR; PG8_SCHED;
;             PG8_LDA(At, 1, 1); PG8_STAGE(PG8_SB(1, 0), b3, voffB); PG8_STAGE(PG8_SB(1, 1), b3 + hstep, voffB); PG8_STAGE(PG8_SA(1, 0), a3, voffA);
;             PG8_WAIT_V(8); PG8_WAIT_L(0); PG8_BAR; PG8_MMA(1, 0, At, B0); PG8_MMA(1, 1, At, B1); PG8_BAR; PG8_SCHED;
	s_add_i32 s25, 0, 0x18000
	s_add_i32 s30, 0, 0x1c000
	ds_read_b128 v[146:149], v141 offset:32768
	ds_read_b128 v[150:153], v141 offset:33792
	ds_read_b128 v[154:157], v141 offset:34816
	ds_read_b128 v[158:161], v141 offset:35840
	ds_read_b128 v[168:171], v141 offset:49152
	ds_read_b128 v[172:175], v141 offset:50176
	ds_read_b128 v[176:179], v141 offset:51200
	ds_read_b128 v[180:183], v141 offset:52224
	s_add_u32 s26, s64, 0x80000
	s_addc_u32 s27, s65, 0
	s_mov_b32 m0, s47
	ds_read_b128 v[184:187], v145 offset:32768
	ds_read_b128 v[188:191], v145 offset:33792
	ds_read_b128 v[192:195], v145 offset:34816
	ds_read_b128 v[196:199], v145 offset:35840
	ds_read_b128 v[200:203], v145 offset:36864
	ds_read_b128 v[224:227], v145 offset:37888
	ds_read_b128 v[228:231], v145 offset:38912
	ds_read_b128 v[232:235], v145 offset:39936
	global_load_lds_dwordx4 v134, s[26:27]
	s_mov_b32 m0, s77
	s_nop 0
	global_load_lds_dwordx4 v132, s[26:27]
	s_waitcnt vmcnt(8)
	s_waitcnt lgkmcnt(0)
	s_barrier
	s_setprio 1
	v_mfma_f32_16x16x32_bf16 v[126:129], v[146:149], v[184:187], v[126:129]
	v_mfma_f32_16x16x32_bf16 v[126:129], v[150:153], v[188:191], v[126:129]
	v_mfma_f32_16x16x32_bf16 v[118:121], v[154:157], v[184:187], v[118:121]
	v_mfma_f32_16x16x32_bf16 v[118:121], v[158:161], v[188:191], v[118:121]
	v_mfma_f32_16x16x32_bf16 v[110:113], v[146:149], v[192:195], v[110:113]
	v_mfma_f32_16x16x32_bf16 v[110:113], v[150:153], v[196:199], v[110:113]
	v_mfma_f32_16x16x32_bf16 v[102:105], v[154:157], v[192:195], v[102:105]
	v_mfma_f32_16x16x32_bf16 v[102:105], v[158:161], v[196:199], v[102:105]
	v_mfma_f32_16x16x32_bf16 v[94:97], v[146:149], v[200:203], v[94:97]
	v_mfma_f32_16x16x32_bf16 v[94:97], v[150:153], v[224:227], v[94:97]
	v_mfma_f32_16x16x32_bf16 v[86:89], v[154:157], v[200:203], v[86:89]
	v_mfma_f32_16x16x32_bf16 v[86:89], v[158:161], v[224:227], v[86:89]
	v_mfma_f32_16x16x32_bf16 v[78:81], v[146:149], v[228:231], v[78:81]
	v_mfma_f32_16x16x32_bf16 v[78:81], v[150:153], v[232:235], v[78:81]
	v_mfma_f32_16x16x32_bf16 v[70:73], v[154:157], v[228:231], v[70:73]
	v_mfma_f32_16x16x32_bf16 v[70:73], v[158:161], v[232:235], v[70:73]
	v_mfma_f32_16x16x32_bf16 v[122:125], v[168:171], v[184:187], v[122:125]
	v_mfma_f32_16x16x32_bf16 v[122:125], v[172:175], v[188:191], v[122:125]
	v_mfma_f32_16x16x32_bf16 v[114:117], v[176:179], v[184:187], v[114:117]
	v_mfma_f32_16x16x32_bf16 v[114:117], v[180:183], v[188:191], v[114:117]
	v_mfma_f32_16x16x32_bf16 v[106:109], v[168:171], v[192:195], v[106:109]
	v_mfma_f32_16x16x32_bf16 v[106:109], v[172:175], v[196:199], v[106:109]
	v_mfma_f32_16x16x32_bf16 v[98:101], v[176:179], v[192:195], v[98:101]
	v_mfma_f32_16x16x32_bf16 v[98:101], v[180:183], v[196:199], v[98:101]
	v_mfma_f32_16x16x32_bf16 v[90:93], v[168:171], v[200:203], v[90:93]
	v_mfma_f32_16x16x32_bf16 v[90:93], v[172:175], v[224:227], v[90:93]
	v_mfma_f32_16x16x32_bf16 v[82:85], v[176:179], v[200:203], v[82:85]
	v_mfma_f32_16x16x32_bf16 v[82:85], v[180:183], v[224:227], v[82:85]
	v_mfma_f32_16x16x32_bf16 v[74:77], v[168:171], v[228:231], v[74:77]
	v_mfma_f32_16x16x32_bf16 v[74:77], v[172:175], v[232:235], v[74:77]
	v_mfma_f32_16x16x32_bf16 v[66:69], v[176:179], v[228:231], v[66:69]
	v_mfma_f32_16x16x32_bf16 v[66:69], v[180:183], v[232:235], v[66:69]
	s_setprio 0
	s_barrier
	s_add_i32 s25, s25, s74
	s_mov_b32 m0, s25
	ds_read_b128 v[184:187], v145 offset:49152
	ds_read_b128 v[188:191], v145 offset:50176
	ds_read_b128 v[192:195], v145 offset:51200
	ds_read_b128 v[196:199], v145 offset:52224
	ds_read_b128 v[200:203], v145 offset:53248
	ds_read_b128 v[224:227], v145 offset:54272
	ds_read_b128 v[228:231], v145 offset:55296
	ds_read_b128 v[232:235], v145 offset:56320
	s_add_u32 s26, s58, 0x80
	s_addc_u32 s27, s59, 0
	global_load_lds_dwordx4 v0, s[26:27]
	s_add_i32 m0, s25, 0x2000
	s_add_i32 s25, s30, s74
	global_load_lds_dwordx4 v130, s[26:27]
	s_add_u32 s26, s58, 0x80080
	s_addc_u32 s27, s59, 0
	s_mov_b32 m0, s25
	s_nop 0
	global_load_lds_dwordx4 v0, s[26:27]
	s_add_i32 m0, s25, 0x2000
	s_nop 0
	global_load_lds_dwordx4 v130, s[26:27]
	s_add_u32 s26, s64, 0x80
	s_addc_u32 s27, s65, 0
	s_mov_b32 m0, s62
	s_nop 0
	global_load_lds_dwordx4 v134, s[26:27]
	s_mov_b32 m0, s63
	s_nop 0
	global_load_lds_dwordx4 v132, s[26:27]
	s_waitcnt vmcnt(8)
	s_waitcnt lgkmcnt(0)
	s_barrier
	s_setprio 1
	v_mfma_f32_16x16x32_bf16 v[62:65], v[146:149], v[184:187], v[62:65]
	v_mfma_f32_16x16x32_bf16 v[62:65], v[150:153], v[188:191], v[62:65]
	v_mfma_f32_16x16x32_bf16 v[54:57], v[154:157], v[184:187], v[54:57]
	v_mfma_f32_16x16x32_bf16 v[54:57], v[158:161], v[188:191], v[54:57]
	v_mfma_f32_16x16x32_bf16 v[46:49], v[146:149], v[192:195], v[46:49]
	v_mfma_f32_16x16x32_bf16 v[46:49], v[150:153], v[196:199], v[46:49]
	v_mfma_f32_16x16x32_bf16 v[38:41], v[154:157], v[192:195], v[38:41]
	v_mfma_f32_16x16x32_bf16 v[38:41], v[158:161], v[196:199], v[38:41]
	v_mfma_f32_16x16x32_bf16 v[30:33], v[146:149], v[200:203], v[30:33]
	v_mfma_f32_16x16x32_bf16 v[30:33], v[150:153], v[224:227], v[30:33]
	v_mfma_f32_16x16x32_bf16 v[22:25], v[154:157], v[200:203], v[22:25]
	v_mfma_f32_16x16x32_bf16 v[22:25], v[158:161], v[224:227], v[22:25]
	v_mfma_f32_16x16x32_bf16 v[14:17], v[146:149], v[228:231], v[14:17]
	v_mfma_f32_16x16x32_bf16 v[14:17], v[150:153], v[232:235], v[14:17]
	v_mfma_f32_16x16x32_bf16 v[6:9], v[154:157], v[228:231], v[6:9]
	v_mfma_f32_16x16x32_bf16 v[6:9], v[158:161], v[232:235], v[6:9]
	v_mfma_f32_16x16x32_bf16 v[58:61], v[168:171], v[184:187], v[58:61]
	v_mfma_f32_16x16x32_bf16 v[58:61], v[172:175], v[188:191], v[58:61]
	v_mfma_f32_16x16x32_bf16 v[50:53], v[176:179], v[184:187], v[50:53]
	v_mfma_f32_16x16x32_bf16 v[50:53], v[180:183], v[188:191], v[50:53]
	v_mfma_f32_16x16x32_bf16 v[42:45], v[168:171], v[192:195], v[42:45]
	v_mfma_f32_16x16x32_bf16 v[42:45], v[172:175], v[196:199], v[42:45]
	v_mfma_f32_16x16x32_bf16 v[34:37], v[176:179], v[192:195], v[34:37]
	v_mfma_f32_16x16x32_bf16 v[34:37], v[180:183], v[196:199], v[34:37]
	v_mfma_f32_16x16x32_bf16 v[26:29], v[168:171], v[200:203], v[26:29]
	v_mfma_f32_16x16x32_bf16 v[26:29], v[172:175], v[224:227], v[26:29]
	v_mfma_f32_16x16x32_bf16 v[18:21], v[176:179], v[200:203], v[18:21]
	v_mfma_f32_16x16x32_bf16 v[18:21], v[180:183], v[224:227], v[18:21]
	v_mfma_f32_16x16x32_bf16 v[10:13], v[168:171], v[228:231], v[10:13]
	v_mfma_f32_16x16x32_bf16 v[10:13], v[172:175], v[232:235], v[10:13]
	v_mfma_f32_16x16x32_bf16 v[2:5], v[176:179], v[228:231], v[2:5]
	v_mfma_f32_16x16x32_bf16 v[2:5], v[180:183], v[232:235], v[2:5]
	s_setprio 0
	s_barrier
	s_add_i32 s24, s24, 2
	s_add_u32 s56, s56, 0x100
	s_addc_u32 s57, s57, 0
	s_add_u32 s14, s14, 0x100
	s_addc_u32 s15, s15, 0
	s_cmp_gt_u32 s24, 29
	s_cbranch_scc0 .LBB0_193
	s_and_b64 vcc, exec, s[40:41]
	s_cbranch_vccz .LBB0_196
	s_barrier
